# grid barrier: acquire L1 invalidate issued at arrival (overlaps the wait) instead of after the release flag, leaders and non-leaders
# speedup vs baseline: 1.0181x; 1.0030x over previous
.LBB0_646:
	s_or_b64 exec, exec, s[4:5]
	v_cvt_f32_u32_e32 v5, v3
	s_waitcnt vmcnt(0)
	v_readfirstlane_b32 s2, v4
	v_sub_u32_e32 v4, 0, v3
	v_rcp_iflag_f32_e32 v5, v5
	v_add_u32_e32 v6, s2, v0
	v_mul_f32_e32 v5, 0x4f7ffffe, v5
	v_cvt_u32_f32_e32 v5, v5
	v_mul_lo_u32 v0, v4, v5
	v_mul_hi_u32 v0, v5, v0
	v_add_u32_e32 v0, v5, v0
	v_mul_hi_u32 v0, v6, v0
	v_mul_lo_u32 v4, v0, v3
	v_sub_u32_e32 v4, v6, v4
	v_add_u32_e32 v5, 1, v0
	v_cmp_ge_u32_e32 vcc, v4, v3
	s_nop 1
	v_cndmask_b32_e32 v0, v0, v5, vcc
	v_sub_u32_e32 v5, v4, v3
	v_cndmask_b32_e32 v4, v4, v5, vcc
	v_add_u32_e32 v5, 1, v0
	v_cmp_ge_u32_e32 vcc, v4, v3
	v_add_u32_e32 v4, 1, v6
	s_nop 0
	v_cndmask_b32_e32 v0, v0, v5, vcc
	v_mul_lo_u32 v5, v3, v0
	v_add_u32_e32 v3, v5, v3
	v_cmp_ne_u32_e32 vcc, v4, v3
	s_and_saveexec_b64 s[2:3], vcc
	s_xor_b64 s[4:5], exec, s[2:3]
	s_cbranch_execz .LBB0_660
	v_readlane_b32 s2, v247, 15
	v_readlane_b32 s3, v247, 16
	s_waitcnt lgkmcnt(0)
	s_nop 3
	buffer_inv sc1
	global_load_dword v2, v1, s[2:3] sc1
	s_waitcnt vmcnt(0)
	v_cmp_eq_u32_e32 vcc, v2, v0
	s_and_saveexec_b64 s[6:7], vcc
	s_cbranch_execz .LBB0_659
	s_mov_b32 s2, 1
	s_mov_b64 s[8:9], 0
	s_branch .LBB0_650

.LBB0_659:
	s_or_b64 exec, exec, s[6:7]
	s_waitcnt vmcnt(0)
	s_waitcnt vmcnt(0)

.LBB0_663:
	s_or_b64 exec, exec, s[6:7]
	buffer_inv sc1
	s_waitcnt vmcnt(0)
	v_readfirstlane_b32 s2, v3
	v_sub_u32_e32 v4, 0, v2
	s_mov_b64 s[6:7], -1
	v_add_u32_e32 v3, s2, v0
	v_cvt_f32_u32_e32 v0, v2
	v_readlane_b32 s2, v247, 19
	v_readlane_b32 s3, v247, 20
	v_rcp_iflag_f32_e32 v0, v0
	s_nop 0
	v_mul_f32_e32 v0, 0x4f7ffffe, v0
	v_cvt_u32_f32_e32 v0, v0
	v_mul_lo_u32 v4, v4, v0
	v_mul_hi_u32 v4, v0, v4
	v_add_u32_e32 v0, v0, v4
	v_mul_hi_u32 v0, v3, v0
	v_mul_lo_u32 v4, v0, v2
	v_sub_u32_e32 v4, v3, v4
	v_cmp_ge_u32_e32 vcc, v4, v2
	v_add_u32_e32 v5, 1, v0
	v_add_u32_e32 v3, 1, v3
	v_cndmask_b32_e32 v0, v0, v5, vcc
	v_sub_u32_e32 v5, v4, v2
	v_cndmask_b32_e32 v4, v4, v5, vcc
	v_cmp_ge_u32_e32 vcc, v4, v2
	v_add_u32_e32 v4, 1, v0
	s_nop 0
	v_cndmask_b32_e32 v0, v0, v4, vcc
	v_mul_lo_u32 v4, v2, v0
	v_add_u32_e32 v2, v4, v2
	v_cmp_ne_u32_e32 vcc, v3, v2
	v_mov_b64_e32 v[2:3], s[2:3]
	s_and_saveexec_b64 s[4:5], vcc
	s_cbranch_execz .LBB0_675
	v_readlane_b32 s2, v247, 19
	v_readlane_b32 s3, v247, 20
	s_mov_b64 s[8:9], 0
	s_nop 3
	global_load_dword v2, v1, s[2:3] sc1
	s_waitcnt vmcnt(0)
	v_cmp_eq_u32_e32 vcc, v2, v0
	s_and_saveexec_b64 s[6:7], vcc
	s_cbranch_execz .LBB0_674
	s_mov_b32 s2, 1
	s_branch .LBB0_667

.LBB0_677:
	s_or_b64 exec, exec, s[4:5]
	s_mov_b64 s[4:5], exec
	v_mbcnt_lo_u32_b32 v0, s4, 0
	v_mbcnt_hi_u32_b32 v0, s5, v0
	v_cmp_eq_u32_e32 vcc, 0, v0
	s_waitcnt vmcnt(0)
	s_and_saveexec_b64 s[6:7], vcc
	s_cbranch_execnz .LBB0_678
	s_getpc_b64 s[98:99]
